# v27 plus loop-edge edit of the indexer select loop: per-pass T/done update and exit tests in 9 instructions instead of 19
# speedup vs baseline: 1.0041x; 1.0007x over previous
.Lidxsel_sum:
	v_add3_u32 v6, v6, v7, v8
	s_nop 1
	v_add_u32_dpp v6, v6, v6 quad_perm:[1,0,3,2] row_mask:0xf bank_mask:0xf
	s_nop 1
	v_add_u32_dpp v6, v6, v6 quad_perm:[2,3,0,1] row_mask:0xf bank_mask:0xf
	s_nop 1
	v_add_u32_dpp v6, v6, v6 row_ror:4 row_mask:0xf bank_mask:0xf
	s_nop 1
	v_add_u32_dpp v6, v6, v6 row_ror:8 row_mask:0xf bank_mask:0xf
	v_mov_b32_e32 v7, v6
	s_nop 1
	v_permlane16_swap_b32_e32 v7, v6
	v_add_u32_e32 v6, v6, v7
	v_cmp_le_i32_e32 vcc, s33, v6
	s_andn2_b64 s[82:83], vcc, s[74:75]
	v_cmp_eq_u32_e32 vcc, s33, v6
	v_cndmask_b32_e64 v66, v66, v5, s[82:83]
	s_and_b64 vcc, vcc, s[82:83]
	s_or_b64 s[74:75], s[74:75], vcc
	v_cmp_ne_u32_e32 vcc, -1, v2
	s_cbranch_vccz .LBB0_398
.LBB0_654:
	s_andn2_b64 vcc, exec, s[74:75]
	s_cbranch_vccnz .LBB0_652
	s_branch .LBB0_398
